# removed cg grid.sync body; P5 S5 pass-1 scan rewritten: transposed Bu MFMA + permlane32_swap, f32 Bu in registers, no LDS round trip
# speedup vs baseline: 1.0083x; 1.0083x over previous
; #define LAS __attribute__((address_space(3)))
;     __device__ __forceinline__ const float* in(int i) const { return karg_in(i); }
; #define FTID const int ftid_ = fresh_tid()
; #define WAVE (__builtin_amdgcn_readfirstlane(ftid_ >> 6))
; __device__ __forceinline__ void p0_prologue(const Ctx& C, LAS unsigned char* lds, int wave, int lane, int tid) {
;     LAS float* tile = (LAS float*)lds;
;     const int gw = blockIdx.x * NWAVES + wave, NGW = gridDim.x * NWAVES;
;     constexpr int I_GU = (DM / 64) * (DFF / 256), I_D = (DFF / 64) * (DM / 256), I_IN = (DM / 64) * (DIN / 256), I_GLU = (BWD / 64) * (BWD / 256), I_OUT = (DM / 64) * (DM / 256);
;     constexpr int NITEMS = 4 * I_GU + 2 * I_D + I_IN + I_GLU + I_OUT;
;     for (int it = blockIdx.x; it < NITEMS; it += gridDim.x) {
;         int r = it;
;         if (r < I_GU) { p0_block_item(C.in(5), C.in(4), DM, DFF, C.Wgu1(), 1, r, tile, tid); continue; } r -= I_GU;
;         if (r < I_GU) { p0_block_item(C.in(6), C.in(4), DM, DFF, C.Wgu1(), 2, r, tile, tid); continue; } r -= I_GU;
;         if (r < I_GU) { p0_block_item(C.in(29), C.in(28), DM, DFF, C.Wgu2(), 1, r, tile, tid); continue; } r -= I_GU;
;         if (r < I_GU) { p0_block_item(C.in(30), C.in(28), DM, DFF, C.Wgu2(), 2, r, tile, tid); continue; } r -= I_GU;
;         if (r < I_D) { p0_block_item(C.in(7), nullptr, DFF, DM, C.Wd1(), 0, r, tile, tid); continue; } r -= I_D;
;         if (r < I_D) { p0_block_item(C.in(31), nullptr, DFF, DM, C.Wd2(), 0, r, tile, tid); continue; } r -= I_D;
;         if (r < I_IN) { p0_block_item(C.in(10), C.in(9), DM, DIN, C.Win(), 0, r, tile, tid); continue; } r -= I_IN;
;         if (r < I_GLU) { p0_block_item(C.in(22), nullptr, BWD, BWD, C.Wglu(), 0, r, tile, tid); continue; } r -= I_GLU;
;         p0_block_item(C.in(26), nullptr, DM, DM, C.Wout(), 0, r, tile, tid);
; __global__ void __launch_bounds__(NTHREADS, 2) fwd_kernel(Args args) {
;     ...
;     grid.sync();
;     { FTID; p0_prologue(C, lds, WAVE, LANE, TID); }
.LBB0_5:
	s_or_b64 exec, exec, s[4:5]
	v_lshrrev_b32_e32 v1, 20, v0
	v_lshrrev_b32_e32 v0, 10, v0
	v_or_b32_e32 v0, v0, v1
	s_movk_i32 s0, 0x3ff
	v_and_or_b32 v0, v0, s0, v182
	v_cmp_eq_u32_e32 vcc, 0, v0
	s_barrier
	s_and_saveexec_b64 s[4:5], vcc
.LBB0_15:
	s_or_b64 exec, exec, s[4:5]
	v_mov_b32_e32 v84, v182
	s_barrier
	s_cmpk_gt_i32 s33, 0x4cf
	v_readfirstlane_b32 s3, v84
	s_cbranch_scc1 .LBB0_60
	v_lshlrev_b32_e32 v0, 2, v84
	v_ashrrev_i32_e32 v38, 6, v84
	v_and_b32_e32 v0, 0xfc, v0
	s_movk_i32 s0, 0x404
	v_lshlrev_b32_e32 v1, 2, v0
	v_mul_lo_u32 v2, v38, s0
	v_add3_u32 v39, 0, v1, v2
	v_lshlrev_b32_e32 v1, 3, v84
	v_ashrrev_i32_e32 v40, 3, v84
	v_and_b32_e32 v2, 56, v1
	v_mul_u32_u24_e32 v1, 0x404, v2
	v_lshlrev_b32_e32 v3, 2, v40
	v_add_u32_e32 v42, 64, v40
	v_add_u32_e32 v44, 0xc0, v40
	v_add3_u32 v41, 0, v1, v3
	v_and_b32_e32 v45, 0x7f, v40
	v_and_b32_e32 v46, 0x7f, v42
	v_and_b32_e32 v47, 0x7f, v44
	v_lshlrev_b32_e32 v1, 1, v40
	s_lshl_b32 s0, s33, 4
	v_mov_b32_e32 v33, 0
	v_add_u32_e32 v43, 0x80, v40
	v_or_b32_e32 v48, 0x80, v45
	v_or_b32_e32 v49, 0x80, v46
	v_or_b32_e32 v50, 0x80, v47
	v_lshl_add_u32 v51, s33, 9, v1
	s_lshl_b32 s24, s44, 9
	s_lshl_b32 s25, s33, 8
	s_lshl_b32 s26, s44, 8
	s_add_i32 s27, s0, 0x700
	s_lshl_b32 s28, s44, 4
	s_lshl_b32 s29, s33, 5
	s_lshl_b32 s30, s44, 5
	s_mov_b32 s31, 0x8000
	s_mov_b32 s0, 0x10000
	s_mov_b32 s34, 0x18000
	s_mov_b32 s35, 0x20000
	s_mov_b32 s36, 0x28000
	s_mov_b32 s37, 0x30000
	s_mov_b32 s38, 0x38000
	v_add_u32_e32 v52, 0x2020, v39
	v_add_u32_e32 v53, 0x2028, v39
	v_add_u32_e32 v54, 0x4040, v39
	v_add_u32_e32 v55, 0x4048, v39
	v_add_u32_e32 v56, 0x6060, v39
	v_add_u32_e32 v57, 0x6068, v39
	v_add_u32_e32 v58, 0x8080, v39
	v_add_u32_e32 v59, 0x8088, v39
	v_add_u32_e32 v60, 0xa0a0, v39
	v_add_u32_e32 v61, 0xa0a8, v39
	v_add_u32_e32 v62, 0xc0c0, v39
	v_add_u32_e32 v63, 0xc0c8, v39
	v_add_u32_e32 v64, 0xe0e0, v39
	v_add_u32_e32 v65, 0xe0e8, v39
	s_mov_b64 s[4:5], 0x1600000
	s_movk_i32 s39, 0x4000
	s_mov_b32 s40, 0xc000
	s_mov_b32 s41, 0x14000
	s_mov_b32 s42, 0x1c000
	s_mov_b64 s[6:7], 0x1500000
	s_movk_i32 s43, 0x1800
	s_mov_b64 s[8:9], 0x1200000
	s_mov_b64 s[10:11], 0x2300000
	s_movk_i32 s46, 0x1600
	s_mov_b64 s[12:13], 0xc00000
	s_movk_i32 s47, 0x2c00
	s_mov_b64 s[14:15], 0x1800000
	s_movk_i32 s48, 0xff00
	s_mov_b64 s[16:17], 0x100000
	v_lshlrev_b32_e32 v32, 2, v0
	v_lshlrev_b32_e32 v34, 1, v2
	v_add_u32_e32 v66, 4, v41
	v_add_u32_e32 v67, 8, v41
	v_add_u32_e32 v68, 12, v41
	v_add_u32_e32 v69, 16, v41
	v_add_u32_e32 v70, 20, v41
	v_add_u32_e32 v71, 24, v41
	v_add_u32_e32 v72, 28, v41
	s_mov_b32 s49, s33
	s_branch .LBB0_19

;     __device__ __forceinline__ const float* in(int i) const { return karg_in(i); }
; template <bool PASS2>
; __device__ __forceinline__ void s5_tile(const Ctx& C, int T, int sb_lo, int sb_hi, LAS unsigned char* lds, int wave, int lane) {
;     ...
;     const float* LAM = C.LAM();
;     const bf16* Zb = C.Z() + (size_t)1024 + 64 * wave;
;     float sr[4], si[4], lr[4], li[4], dsk[4];
; #pragma unroll
;     for (int gi = 0; gi < 4; ++gi) { const int g = wave * 4 + gi; sr[gi] = 0.f; si[gi] = 0.f; lr[gi] = LAM[0 * 2048 + g * 64 + lane]; li[gi] = LAM[1 * 2048 + g * 64 + lane];
;         dsk[gi] = PASS2 ? C.in(21)[16 * g + fr] : 0.f; }
;     if (PASS2 && !sample) {
;         const int k = T & 127, tb = T - k;
;         float l8r[4], l8i[4];
; #pragma unroll
;         for (int gi = 0; gi < 4; ++gi) { l8r[gi] = LAM[2 * 2048 + (wave * 4 + gi) * 64 + lane]; l8i[gi] = LAM[3 * 2048 + (wave * 4 + gi) * 64 + lane]; }
;         const v2f* Ep = (const v2f*)C.E() + ((size_t)tb * NG + wave * 4) * NP + lane;
;         const int nb = (k + 15) >> 4, j0 = k - 16 * nb;
;         for (int jb = 0; jb < nb; ++jb) {
; #pragma unroll
;             for (int u = 0; u < 16; ++u) {
;                 const int j = j0 + 16 * jb + u; const bool ok = j >= 0; const int jc = ok ? j : 0;
; #pragma unroll
;                 for (int gi = 0; gi < 4; ++gi) { v2f e = Ep[(size_t)jc * NG * NP + gi * NP]; if (!ok) e = (v2f){0.f, 0.f};
;                     const float nr = fmaf(l8r[gi], sr[gi], fmaf(-l8i[gi], si[gi], e.x)), ni = fmaf(l8r[gi], si[gi], fmaf(l8i[gi], sr[gi], e.y)); sr[gi] = nr; si[gi] = ni; }
;             }
;         }
;     }
;     v4u xn[4];
;     {
;         const int sb0 = sb_lo;
; #pragma unroll
;         for (int i = 0; i < 4; ++i) xn[i] = *(const v4u*)(Zb + (size_t)(r0 + 32 * sb0 + xrow + 8 * i) * DIN + 8 * xpart);
;     }
;     const bf16* BBt = C.BB(); const bf16* CMt = C.CM();
;     bfx8 bbn[4], cmn[4];
; #pragma unroll
;     for (int cb = 0; cb < 4; ++cb) bbn[cb] = *(const bfx8*)(BBt + ((size_t)(wave * 4 * 128 + cb * 32 + tl)) * GN + 8 * hh);
;     if (PASS2) {
; #pragma unroll
;         for (int ks = 0; ks < 4; ++ks) cmn[ks] = *(const bfx8*)(CMt + ((size_t)(wave * 4 * GN + fr)) * 128 + 32 * ks + 8 * kq);
;     }
;     for (int sb = sb_lo; sb < sb_hi; ++sb) {
.LBB0_595:
	s_mov_b64 s[0:1], s[80:81]
	s_load_dwordx2 s[0:1], s[0:1], 0x110
	v_readfirstlane_b32 s13, v81
	s_ashr_i32 s42, s13, 6
	s_mul_i32 s3, s42, 0x3400
	s_add_i32 s3, s3, 0
	s_waitcnt lgkmcnt(0)
	s_add_u32 s0, s0, 0x2a40000
	s_addc_u32 s1, s1, 0
	s_lshl_b32 s25, s42, 8
	s_mov_b64 s[26:27], s[80:81]
	v_add_u32_e32 v2, s25, v89
	v_ashrrev_i32_e32 v3, 31, v2
	s_load_dwordx2 s[28:29], s[26:27], 0x110
	v_lshl_add_u64 v[2:3], v[2:3], 2, s[0:1]
	s_or_b32 s26, s25, 64
	v_or_b32_e32 v0, s25, v80
	global_load_dword v65, v[2:3], off
	v_or_b32_e32 v2, s26, v80
	v_add_u32_e32 v4, s26, v89
	s_or_b32 s26, s25, 0x80
	s_or_b32 s25, s25, 0xc0
	s_and_b32 s52, s13, 0xffffffc0
	v_or_b32_e32 v6, s26, v80
	v_add_u32_e32 v8, s26, v89
	v_or_b32_e32 v10, s25, v80
	v_add_u32_e32 v12, s25, v89
	s_ashr_i32 s53, s52, 31
	v_ashrrev_i32_e32 v1, 31, v0
	v_ashrrev_i32_e32 v3, 31, v2
	v_ashrrev_i32_e32 v5, 31, v4
	v_ashrrev_i32_e32 v7, 31, v6
	v_ashrrev_i32_e32 v9, 31, v8
	v_ashrrev_i32_e32 v11, 31, v10
	v_ashrrev_i32_e32 v13, 31, v12
	v_lshl_add_u64 v[0:1], v[0:1], 2, s[0:1]
	v_lshl_add_u64 v[2:3], v[2:3], 2, s[0:1]
	v_lshl_add_u64 v[4:5], v[4:5], 2, s[0:1]
	v_lshl_add_u64 v[6:7], v[6:7], 2, s[0:1]
	v_lshl_add_u64 v[8:9], v[8:9], 2, s[0:1]
	v_lshl_add_u64 v[10:11], v[10:11], 2, s[0:1]
	v_lshl_add_u64 v[12:13], v[12:13], 2, s[0:1]
	s_lshl_b32 s26, s24, 7
	s_lshl_b64 s[0:1], s[52:53], 1
	s_waitcnt lgkmcnt(0)
	s_add_u32 s0, s28, s0
	s_addc_u32 s1, s29, s1
	global_load_dword v66, v[0:1], off
	global_load_dword v68, v[2:3], off
	global_load_dword v71, v[4:5], off
	global_load_dword v72, v[6:7], off
	global_load_dword v75, v[8:9], off
	global_load_dword v76, v[10:11], off
	global_load_dword v79, v[12:13], off
	v_or_b32_e32 v4, s26, v87
	v_lshl_add_u64 v[0:1], s[0:1], 0, v[94:95]
	v_lshl_add_u64 v[102:103], v[0:1], 0, s[14:15]
	v_or_b32_e32 v2, 8, v4
	v_mad_i64_i32 v[0:1], s[0:1], v4, s34, v[102:103]
	v_mad_i64_i32 v[2:3], s[0:1], v2, s34, v[102:103]
	global_load_dwordx4 v[16:19], v[0:1], off
	global_load_dwordx4 v[20:23], v[2:3], off
	v_or_b32_e32 v0, 16, v4
	v_or_b32_e32 v2, 24, v4
	v_mad_i64_i32 v[0:1], s[0:1], v0, s34, v[102:103]
	v_mad_i64_i32 v[2:3], s[0:1], v2, s34, v[102:103]
	s_mov_b64 s[0:1], s[80:81]
	global_load_dwordx4 v[24:27], v[0:1], off
	global_load_dwordx4 v[28:31], v[2:3], off
	s_load_dwordx2 s[0:1], s[0:1], 0x110
	v_lshlrev_b32_e32 v4, 1, v85
	v_lshl_or_b32 v0, s42, 9, v4
	v_ashrrev_i32_e32 v1, 31, v0
	v_lshlrev_b64 v[4:5], 5, v[0:1]
	s_mov_b64 s[28:29], s[80:81]
	s_waitcnt lgkmcnt(0)
	v_lshl_add_u64 v[2:3], s[0:1], 0, v[98:99]
	v_lshl_add_u64 v[2:3], v[2:3], 0, s[16:17]
	v_lshl_add_u64 v[104:105], v[2:3], 0, v[4:5]
	v_or_b32_e32 v4, 0x1, v0
	v_ashrrev_i32_e32 v5, 31, v4
	v_lshlrev_b64 v[4:5], 5, v[4:5]
	v_lshl_add_u64 v[106:107], v[2:3], 0, v[4:5]
	v_or_b32_e32 v4, 0x40, v0
	v_ashrrev_i32_e32 v5, 31, v4
	v_lshlrev_b64 v[4:5], 5, v[4:5]
	v_lshl_add_u64 v[108:109], v[2:3], 0, v[4:5]
	v_or_b32_e32 v4, 0x41, v0
	v_ashrrev_i32_e32 v5, 31, v4
	v_lshlrev_b64 v[4:5], 5, v[4:5]
	global_load_dwordx4 v[44:47], v[104:105], off
	global_load_dwordx4 v[40:43], v[106:107], off
	v_lshl_add_u64 v[110:111], v[2:3], 0, v[4:5]
	global_load_dwordx4 v[36:39], v[108:109], off
	global_load_dwordx4 v[32:35], v[110:111], off
	v_or_b32_e32 v4, 0x80, v0
	v_ashrrev_i32_e32 v5, 31, v4
	v_lshlrev_b64 v[4:5], 5, v[4:5]
	v_lshl_add_u64 v[112:113], v[2:3], 0, v[4:5]
	v_or_b32_e32 v4, 0x81, v0
	v_ashrrev_i32_e32 v5, 31, v4
	v_lshlrev_b64 v[4:5], 5, v[4:5]
	v_lshl_add_u64 v[114:115], v[2:3], 0, v[4:5]
	v_or_b32_e32 v4, 0xc0, v0
	v_ashrrev_i32_e32 v5, 31, v4
	v_lshlrev_b64 v[4:5], 5, v[4:5]
	v_lshl_add_u64 v[116:117], v[2:3], 0, v[4:5]
	v_or_b32_e32 v4, 0xc1, v0
	v_ashrrev_i32_e32 v5, 31, v4
	v_lshlrev_b64 v[4:5], 5, v[4:5]
	v_lshl_add_u64 v[118:119], v[2:3], 0, v[4:5]
	v_or_b32_e32 v4, 0x100, v0
	v_ashrrev_i32_e32 v5, 31, v4
	v_lshlrev_b64 v[4:5], 5, v[4:5]
	v_lshl_add_u64 v[120:121], v[2:3], 0, v[4:5]
	v_or_b32_e32 v4, 0x101, v0
	v_ashrrev_i32_e32 v5, 31, v4
	v_lshlrev_b64 v[4:5], 5, v[4:5]
	v_lshl_add_u64 v[122:123], v[2:3], 0, v[4:5]
	v_or_b32_e32 v4, 0x140, v0
	v_ashrrev_i32_e32 v5, 31, v4
	v_lshlrev_b64 v[4:5], 5, v[4:5]
	v_lshl_add_u64 v[124:125], v[2:3], 0, v[4:5]
	v_or_b32_e32 v4, 0x141, v0
	v_ashrrev_i32_e32 v5, 31, v4
	v_lshlrev_b64 v[4:5], 5, v[4:5]
	v_lshl_add_u64 v[126:127], v[2:3], 0, v[4:5]
	v_or_b32_e32 v4, 0x180, v0
	v_ashrrev_i32_e32 v5, 31, v4
	v_lshlrev_b64 v[4:5], 5, v[4:5]
	v_lshl_add_u64 v[128:129], v[2:3], 0, v[4:5]
	v_or_b32_e32 v4, 0x181, v0
	v_ashrrev_i32_e32 v5, 31, v4
	v_lshlrev_b64 v[4:5], 5, v[4:5]
	v_lshl_add_u64 v[130:131], v[2:3], 0, v[4:5]
	v_or_b32_e32 v4, 0x1c0, v0
	v_or_b32_e32 v0, 0x1c1, v0
	s_waitcnt vmcnt(15)
	v_xor_b32_e32 v64, 0x80000000, v65
	s_waitcnt vmcnt(12)
	v_xor_b32_e32 v70, 0x80000000, v71
	v_ashrrev_i32_e32 v5, 31, v4
	v_ashrrev_i32_e32 v1, 31, v0
	s_waitcnt vmcnt(10)
	v_xor_b32_e32 v74, 0x80000000, v75
	s_waitcnt vmcnt(8)
	v_xor_b32_e32 v78, 0x80000000, v79
	v_add_u32_e32 v6, s3, v91
	v_add_u32_e32 v7, s3, v168
	v_add_u32_e32 v8, s3, v170
	v_lshlrev_b64 v[4:5], 5, v[4:5]
	v_lshlrev_b64 v[0:1], 5, v[0:1]
	v_mov_b32_e32 v144, v65
	v_mov_b32_e32 v145, v64
	v_mov_b32_e32 v148, v71
	v_mov_b32_e32 v149, v70
	v_mov_b32_e32 v152, v75
	v_mov_b32_e32 v153, v74
	v_mov_b32_e32 v156, v79
	v_mov_b32_e32 v157, v78
	v_add_u32_e32 v82, s3, v171
	v_lshl_add_u64 v[132:133], v[2:3], 0, v[4:5]
	v_lshl_add_u64 v[134:135], v[2:3], 0, v[0:1]
	v_mov_b32_e32 v67, v66
	v_pk_mov_b32 v[136:137], v[64:65], v[64:65] op_sel:[1,0]
	v_mov_b32_e32 v69, v68
	v_pk_mov_b32 v[138:139], v[70:71], v[70:71] op_sel:[1,0]
	v_mov_b32_e32 v73, v72
	v_pk_mov_b32 v[140:141], v[74:75], v[74:75] op_sel:[1,0]
	v_mov_b32_e32 v77, v76
	v_pk_mov_b32 v[142:143], v[78:79], v[78:79] op_sel:[1,0]
	v_pk_mov_b32 v[146:147], v[144:145], v[144:145] op_sel:[1,0]
	v_pk_mov_b32 v[150:151], v[148:149], v[148:149] op_sel:[1,0]
	v_pk_mov_b32 v[154:155], v[152:153], v[152:153] op_sel:[1,0]
	v_pk_mov_b32 v[158:159], v[156:157], v[156:157] op_sel:[1,0]
	v_add_u32_e32 v97, v6, v172
	v_add_u32_e32 v101, v7, v169
	v_add_u32_e32 v178, v8, v84
	s_mov_b32 s25, 0
	v_mov_b32_e32 v166, 0
	v_mov_b32_e32 v167, v83
	v_mov_b32_e32 v164, 0
	v_mov_b32_e32 v165, v83
	v_mov_b32_e32 v162, 0
	v_mov_b32_e32 v163, v83
	v_mov_b32_e32 v160, 0
	v_mov_b32_e32 v161, v83
	s_branch .LBB0_597
; #define LAS __attribute__((address_space(3)))
; template <bool PASS2>
; __device__ __forceinline__ void s5_tile(const Ctx& C, int T, int sb_lo, int sb_hi, LAS unsigned char* lds, int wave, int lane) {
;     ...
;         for (int gi = 0; gi < 4; ++gi) {
;             const int g = wave * 4 + gi, gnx = wave * 4 + ((gi + 1) & 3);
;             bfx8 bb[4], cm[4];
; #pragma unroll
;             for (int cb = 0; cb < 4; ++cb) { bb[cb] = bbn[cb]; bbn[cb] = *(const bfx8*)(BBt + ((size_t)(gnx * 128 + cb * 32 + tl)) * GN + 8 * hh); }
;             if (PASS2) {
; #pragma unroll
;                 for (int ks = 0; ks < 4; ++ks) { cm[ks] = cmn[ks]; cmn[ks] = *(const bfx8*)(CMt + ((size_t)(gnx * GN + fr)) * 128 + 32 * ks + 8 * kq); }
;             }
;             float s0ar = 0.f, s0ai = 0.f, s0br = 0.f, s0bi = 0.f;
;             if (sample) { const size_t o0 = ((size_t)(2 * sb) * NG + g) * NP + lane, o1 = o0 + (size_t)NG * NP;
;                 s0ar = C.in(2)[o0]; s0ai = C.in(3)[o0]; s0br = C.in(2)[o1]; s0bi = C.in(3)[o1]; }
;             const bfx8 a = *(const LAS bfx8*)(XU + tl * XU_STRIDE + 16 * gi + 8 * hh);
; #pragma unroll
;             for (int cb = 0; cb < 4; ++cb) {
;                 v16f acc;
; #pragma unroll
;                 for (int r = 0; r < 16; ++r) acc[r] = 0.f;
;                 acc = __builtin_amdgcn_mfma_f32_32x32x16_bf16(bb[cb], a, acc, 0, 0, 0);
; #pragma unroll
;                 for (int rg = 0; rg < 4; ++rg) { v2u w; w.x = cvt_pk_c(acc[4 * rg], acc[4 * rg + 1]); w.y = cvt_pk_c(acc[4 * rg + 2], acc[4 * rg + 3]);
;                     *(LAS v2u*)(BH + tl * BH_STRIDE + cb * 32 + 8 * rg + 4 * hh) = w; }
;             }
;             LDS_FENCE();
;             {
;                 unsigned bu[32];
; #pragma unroll
;                 for (int t = 0; t < 32; ++t) bu[t] = *(const LAS unsigned*)(BH + t * BH_STRIDE + 2 * lane);
;                 LDS_FENCE();
;                 float xr = sr[gi], xi = si[gi];
; #pragma unroll
;                 for (int t = 0; t < 32; ++t) {
;                     if (sample && t == 0) { xr = s0ar; xi = s0ai; }
;                     if (sample && t == 16) { xr = s0br; xi = s0bi; }
;                     const float nr = fmaf(lr[gi], xr, fmaf(-li[gi], xi, bf_lo(bu[t]))), ni = fmaf(lr[gi], xi, fmaf(li[gi], xr, bf_hi(bu[t])));
;                     xr = nr; xi = ni;
;                     if (PASS2) {
.LBB0_596:
	s_waitcnt lgkmcnt(0)
	ds_read_b128 v[224:227], v101
	global_load_dwordx4 v[60:63], v[112:113], off
	global_load_dwordx4 v[56:59], v[114:115], off
	global_load_dwordx4 v[52:55], v[116:117], off
	global_load_dwordx4 v[48:51], v[118:119], off
	s_waitcnt vmcnt(7) lgkmcnt(0)
	v_mfma_f32_32x32x16_bf16 v[0:15], v[224:227], v[44:47], 0
	s_waitcnt vmcnt(6)
	v_mfma_f32_32x32x16_bf16 v[136:151], v[224:227], v[40:43], 0
	s_waitcnt vmcnt(5)
	v_mfma_f32_32x32x16_bf16 v[192:207], v[224:227], v[36:39], 0
	s_waitcnt vmcnt(4)
	v_mfma_f32_32x32x16_bf16 v[208:223], v[224:227], v[32:35], 0
	s_nop 11
	v_permlane32_swap_b32_e32 v0, v192
	v_permlane32_swap_b32_e32 v1, v193
	v_permlane32_swap_b32_e32 v2, v194
	v_permlane32_swap_b32_e32 v3, v195
	v_permlane32_swap_b32_e32 v4, v196
	v_permlane32_swap_b32_e32 v5, v197
	v_permlane32_swap_b32_e32 v6, v198
	v_permlane32_swap_b32_e32 v7, v199
	v_permlane32_swap_b32_e32 v8, v200
	v_permlane32_swap_b32_e32 v9, v201
	v_permlane32_swap_b32_e32 v10, v202
	v_permlane32_swap_b32_e32 v11, v203
	v_permlane32_swap_b32_e32 v12, v204
	v_permlane32_swap_b32_e32 v13, v205
	v_permlane32_swap_b32_e32 v14, v206
	v_permlane32_swap_b32_e32 v15, v207
	v_permlane32_swap_b32_e32 v136, v208
	v_permlane32_swap_b32_e32 v137, v209
	v_permlane32_swap_b32_e32 v138, v210
	v_permlane32_swap_b32_e32 v139, v211
	v_permlane32_swap_b32_e32 v140, v212
	v_permlane32_swap_b32_e32 v141, v213
	v_permlane32_swap_b32_e32 v142, v214
	v_permlane32_swap_b32_e32 v143, v215
	v_permlane32_swap_b32_e32 v144, v216
	v_permlane32_swap_b32_e32 v145, v217
	v_permlane32_swap_b32_e32 v146, v218
	v_permlane32_swap_b32_e32 v147, v219
	v_permlane32_swap_b32_e32 v148, v220
	v_permlane32_swap_b32_e32 v149, v221
	v_permlane32_swap_b32_e32 v150, v222
	v_permlane32_swap_b32_e32 v151, v223
	v_fma_f32 v0, -v65, v166, v0
	v_fma_f32 v136, v65, v167, v136
	v_fma_f32 v167, v66, v167, v0
	v_fma_f32 v166, v66, v166, v136
	v_fma_f32 v1, -v65, v166, v1
	v_fma_f32 v137, v65, v167, v137
	v_fma_f32 v167, v66, v167, v1
	v_fma_f32 v166, v66, v166, v137
	v_fma_f32 v2, -v65, v166, v2
	v_fma_f32 v138, v65, v167, v138
	v_fma_f32 v167, v66, v167, v2
	v_fma_f32 v166, v66, v166, v138
	v_fma_f32 v3, -v65, v166, v3
	v_fma_f32 v139, v65, v167, v139
	v_fma_f32 v167, v66, v167, v3
	v_fma_f32 v166, v66, v166, v139
	v_fma_f32 v192, -v65, v166, v192
	v_fma_f32 v208, v65, v167, v208
	v_fma_f32 v167, v66, v167, v192
	v_fma_f32 v166, v66, v166, v208
	v_fma_f32 v193, -v65, v166, v193
	v_fma_f32 v209, v65, v167, v209
	v_fma_f32 v167, v66, v167, v193
	v_fma_f32 v166, v66, v166, v209
	v_fma_f32 v194, -v65, v166, v194
	v_fma_f32 v210, v65, v167, v210
	v_fma_f32 v167, v66, v167, v194
	v_fma_f32 v166, v66, v166, v210
	v_fma_f32 v195, -v65, v166, v195
	v_fma_f32 v211, v65, v167, v211
	v_fma_f32 v167, v66, v167, v195
	v_fma_f32 v166, v66, v166, v211
	v_fma_f32 v4, -v65, v166, v4
	v_fma_f32 v140, v65, v167, v140
	v_fma_f32 v167, v66, v167, v4
	v_fma_f32 v166, v66, v166, v140
	v_fma_f32 v5, -v65, v166, v5
	v_fma_f32 v141, v65, v167, v141
	v_fma_f32 v167, v66, v167, v5
	v_fma_f32 v166, v66, v166, v141
	v_fma_f32 v6, -v65, v166, v6
	v_fma_f32 v142, v65, v167, v142
	v_fma_f32 v167, v66, v167, v6
	v_fma_f32 v166, v66, v166, v142
	v_fma_f32 v7, -v65, v166, v7
	v_fma_f32 v143, v65, v167, v143
	v_fma_f32 v167, v66, v167, v7
	v_fma_f32 v166, v66, v166, v143
	v_fma_f32 v196, -v65, v166, v196
	v_fma_f32 v212, v65, v167, v212
	v_fma_f32 v167, v66, v167, v196
	v_fma_f32 v166, v66, v166, v212
	v_fma_f32 v197, -v65, v166, v197
	v_fma_f32 v213, v65, v167, v213
	v_fma_f32 v167, v66, v167, v197
	v_fma_f32 v166, v66, v166, v213
	v_fma_f32 v198, -v65, v166, v198
	v_fma_f32 v214, v65, v167, v214
	v_fma_f32 v167, v66, v167, v198
	v_fma_f32 v166, v66, v166, v214
	v_fma_f32 v199, -v65, v166, v199
	v_fma_f32 v215, v65, v167, v215
	v_fma_f32 v167, v66, v167, v199
	v_fma_f32 v166, v66, v166, v215
	v_fma_f32 v8, -v65, v166, v8
	v_fma_f32 v144, v65, v167, v144
	v_fma_f32 v167, v66, v167, v8
	v_fma_f32 v166, v66, v166, v144
	v_fma_f32 v9, -v65, v166, v9
	v_fma_f32 v145, v65, v167, v145
	v_fma_f32 v167, v66, v167, v9
	v_fma_f32 v166, v66, v166, v145
	v_fma_f32 v10, -v65, v166, v10
	v_fma_f32 v146, v65, v167, v146
	v_fma_f32 v167, v66, v167, v10
	v_fma_f32 v166, v66, v166, v146
	v_fma_f32 v11, -v65, v166, v11
	v_fma_f32 v147, v65, v167, v147
	v_fma_f32 v167, v66, v167, v11
	v_fma_f32 v166, v66, v166, v147
	v_fma_f32 v200, -v65, v166, v200
	v_fma_f32 v216, v65, v167, v216
	v_fma_f32 v167, v66, v167, v200
	v_fma_f32 v166, v66, v166, v216
	v_fma_f32 v201, -v65, v166, v201
	v_fma_f32 v217, v65, v167, v217
	v_fma_f32 v167, v66, v167, v201
	v_fma_f32 v166, v66, v166, v217
	v_fma_f32 v202, -v65, v166, v202
	v_fma_f32 v218, v65, v167, v218
	v_fma_f32 v167, v66, v167, v202
	v_fma_f32 v166, v66, v166, v218
	v_fma_f32 v203, -v65, v166, v203
	v_fma_f32 v219, v65, v167, v219
	v_fma_f32 v167, v66, v167, v203
	v_fma_f32 v166, v66, v166, v219
	v_fma_f32 v12, -v65, v166, v12
	v_fma_f32 v148, v65, v167, v148
	v_fma_f32 v167, v66, v167, v12
	v_fma_f32 v166, v66, v166, v148
	v_fma_f32 v13, -v65, v166, v13
	v_fma_f32 v149, v65, v167, v149
	v_fma_f32 v167, v66, v167, v13
	v_fma_f32 v166, v66, v166, v149
	v_fma_f32 v14, -v65, v166, v14
	v_fma_f32 v150, v65, v167, v150
	v_fma_f32 v167, v66, v167, v14
	v_fma_f32 v166, v66, v166, v150
	v_fma_f32 v15, -v65, v166, v15
	v_fma_f32 v151, v65, v167, v151
	v_fma_f32 v167, v66, v167, v15
	v_fma_f32 v166, v66, v166, v151
	v_fma_f32 v204, -v65, v166, v204
	v_fma_f32 v220, v65, v167, v220
	v_fma_f32 v167, v66, v167, v204
	v_fma_f32 v166, v66, v166, v220
	v_fma_f32 v205, -v65, v166, v205
	v_fma_f32 v221, v65, v167, v221
	v_fma_f32 v167, v66, v167, v205
	v_fma_f32 v166, v66, v166, v221
	v_fma_f32 v206, -v65, v166, v206
	v_fma_f32 v222, v65, v167, v222
	v_fma_f32 v167, v66, v167, v206
	v_fma_f32 v166, v66, v166, v222
	v_fma_f32 v207, -v65, v166, v207
	v_fma_f32 v223, v65, v167, v223
	v_fma_f32 v167, v66, v167, v207
	v_fma_f32 v166, v66, v166, v223
	ds_read_b128 v[228:231], v101 offset:32
	global_load_dwordx4 v[44:47], v[120:121], off
	global_load_dwordx4 v[40:43], v[122:123], off
	global_load_dwordx4 v[36:39], v[124:125], off
	global_load_dwordx4 v[32:35], v[126:127], off
	s_waitcnt vmcnt(7) lgkmcnt(0)
; #define LAS __attribute__((address_space(3)))
; template <bool PASS2>
; __device__ __forceinline__ void s5_tile(const Ctx& C, int T, int sb_lo, int sb_hi, LAS unsigned char* lds, int wave, int lane) {
;     ...
;         for (int gi = 0; gi < 4; ++gi) {
;             const int g = wave * 4 + gi, gnx = wave * 4 + ((gi + 1) & 3);
;             bfx8 bb[4], cm[4];
; #pragma unroll
;             for (int cb = 0; cb < 4; ++cb) { bb[cb] = bbn[cb]; bbn[cb] = *(const bfx8*)(BBt + ((size_t)(gnx * 128 + cb * 32 + tl)) * GN + 8 * hh); }
;             if (PASS2) {
; #pragma unroll
;                 for (int ks = 0; ks < 4; ++ks) { cm[ks] = cmn[ks]; cmn[ks] = *(const bfx8*)(CMt + ((size_t)(gnx * GN + fr)) * 128 + 32 * ks + 8 * kq); }
;             }
;             float s0ar = 0.f, s0ai = 0.f, s0br = 0.f, s0bi = 0.f;
;             if (sample) { const size_t o0 = ((size_t)(2 * sb) * NG + g) * NP + lane, o1 = o0 + (size_t)NG * NP;
;                 s0ar = C.in(2)[o0]; s0ai = C.in(3)[o0]; s0br = C.in(2)[o1]; s0bi = C.in(3)[o1]; }
;             const bfx8 a = *(const LAS bfx8*)(XU + tl * XU_STRIDE + 16 * gi + 8 * hh);
; #pragma unroll
;             for (int cb = 0; cb < 4; ++cb) {
;                 v16f acc;
; #pragma unroll
;                 for (int r = 0; r < 16; ++r) acc[r] = 0.f;
;                 acc = __builtin_amdgcn_mfma_f32_32x32x16_bf16(bb[cb], a, acc, 0, 0, 0);
; #pragma unroll
;                 for (int rg = 0; rg < 4; ++rg) { v2u w; w.x = cvt_pk_c(acc[4 * rg], acc[4 * rg + 1]); w.y = cvt_pk_c(acc[4 * rg + 2], acc[4 * rg + 3]);
;                     *(LAS v2u*)(BH + tl * BH_STRIDE + cb * 32 + 8 * rg + 4 * hh) = w; }
;             }
;             LDS_FENCE();
;             {
;                 unsigned bu[32];
; #pragma unroll
;                 for (int t = 0; t < 32; ++t) bu[t] = *(const LAS unsigned*)(BH + t * BH_STRIDE + 2 * lane);
;                 LDS_FENCE();
;                 float xr = sr[gi], xi = si[gi];
; #pragma unroll
;                 for (int t = 0; t < 32; ++t) {
;                     if (sample && t == 0) { xr = s0ar; xi = s0ai; }
;                     if (sample && t == 16) { xr = s0br; xi = s0bi; }
;                     const float nr = fmaf(lr[gi], xr, fmaf(-li[gi], xi, bf_lo(bu[t]))), ni = fmaf(lr[gi], xi, fmaf(li[gi], xr, bf_hi(bu[t])));
;                     xr = nr; xi = ni;
;                     if (PASS2) {
	v_mfma_f32_32x32x16_bf16 v[0:15], v[228:231], v[60:63], 0
	s_waitcnt vmcnt(6)
	v_mfma_f32_32x32x16_bf16 v[136:151], v[228:231], v[56:59], 0
	s_waitcnt vmcnt(5)
	v_mfma_f32_32x32x16_bf16 v[192:207], v[228:231], v[52:55], 0
	s_waitcnt vmcnt(4)
	v_mfma_f32_32x32x16_bf16 v[208:223], v[228:231], v[48:51], 0
	s_nop 11
	v_permlane32_swap_b32_e32 v0, v192
	v_permlane32_swap_b32_e32 v1, v193
	v_permlane32_swap_b32_e32 v2, v194
	v_permlane32_swap_b32_e32 v3, v195
	v_permlane32_swap_b32_e32 v4, v196
	v_permlane32_swap_b32_e32 v5, v197
	v_permlane32_swap_b32_e32 v6, v198
	v_permlane32_swap_b32_e32 v7, v199
	v_permlane32_swap_b32_e32 v8, v200
	v_permlane32_swap_b32_e32 v9, v201
	v_permlane32_swap_b32_e32 v10, v202
	v_permlane32_swap_b32_e32 v11, v203
	v_permlane32_swap_b32_e32 v12, v204
	v_permlane32_swap_b32_e32 v13, v205
	v_permlane32_swap_b32_e32 v14, v206
	v_permlane32_swap_b32_e32 v15, v207
	v_permlane32_swap_b32_e32 v136, v208
	v_permlane32_swap_b32_e32 v137, v209
	v_permlane32_swap_b32_e32 v138, v210
	v_permlane32_swap_b32_e32 v139, v211
	v_permlane32_swap_b32_e32 v140, v212
	v_permlane32_swap_b32_e32 v141, v213
	v_permlane32_swap_b32_e32 v142, v214
	v_permlane32_swap_b32_e32 v143, v215
	v_permlane32_swap_b32_e32 v144, v216
	v_permlane32_swap_b32_e32 v145, v217
	v_permlane32_swap_b32_e32 v146, v218
	v_permlane32_swap_b32_e32 v147, v219
	v_permlane32_swap_b32_e32 v148, v220
	v_permlane32_swap_b32_e32 v149, v221
	v_permlane32_swap_b32_e32 v150, v222
	v_permlane32_swap_b32_e32 v151, v223
	v_fma_f32 v0, -v71, v164, v0
	v_fma_f32 v136, v71, v165, v136
	v_fma_f32 v165, v68, v165, v0
	v_fma_f32 v164, v68, v164, v136
	v_fma_f32 v1, -v71, v164, v1
	v_fma_f32 v137, v71, v165, v137
	v_fma_f32 v165, v68, v165, v1
	v_fma_f32 v164, v68, v164, v137
	v_fma_f32 v2, -v71, v164, v2
	v_fma_f32 v138, v71, v165, v138
	v_fma_f32 v165, v68, v165, v2
	v_fma_f32 v164, v68, v164, v138
	v_fma_f32 v3, -v71, v164, v3
	v_fma_f32 v139, v71, v165, v139
	v_fma_f32 v165, v68, v165, v3
	v_fma_f32 v164, v68, v164, v139
	v_fma_f32 v192, -v71, v164, v192
	v_fma_f32 v208, v71, v165, v208
	v_fma_f32 v165, v68, v165, v192
	v_fma_f32 v164, v68, v164, v208
	v_fma_f32 v193, -v71, v164, v193
	v_fma_f32 v209, v71, v165, v209
	v_fma_f32 v165, v68, v165, v193
	v_fma_f32 v164, v68, v164, v209
	v_fma_f32 v194, -v71, v164, v194
	v_fma_f32 v210, v71, v165, v210
	v_fma_f32 v165, v68, v165, v194
	v_fma_f32 v164, v68, v164, v210
	v_fma_f32 v195, -v71, v164, v195
	v_fma_f32 v211, v71, v165, v211
	v_fma_f32 v165, v68, v165, v195
	v_fma_f32 v164, v68, v164, v211
	v_fma_f32 v4, -v71, v164, v4
	v_fma_f32 v140, v71, v165, v140
	v_fma_f32 v165, v68, v165, v4
	v_fma_f32 v164, v68, v164, v140
	v_fma_f32 v5, -v71, v164, v5
	v_fma_f32 v141, v71, v165, v141
	v_fma_f32 v165, v68, v165, v5
	v_fma_f32 v164, v68, v164, v141
	v_fma_f32 v6, -v71, v164, v6
	v_fma_f32 v142, v71, v165, v142
	v_fma_f32 v165, v68, v165, v6
	v_fma_f32 v164, v68, v164, v142
	v_fma_f32 v7, -v71, v164, v7
	v_fma_f32 v143, v71, v165, v143
	v_fma_f32 v165, v68, v165, v7
	v_fma_f32 v164, v68, v164, v143
	v_fma_f32 v196, -v71, v164, v196
	v_fma_f32 v212, v71, v165, v212
	v_fma_f32 v165, v68, v165, v196
	v_fma_f32 v164, v68, v164, v212
	v_fma_f32 v197, -v71, v164, v197
	v_fma_f32 v213, v71, v165, v213
	v_fma_f32 v165, v68, v165, v197
	v_fma_f32 v164, v68, v164, v213
	v_fma_f32 v198, -v71, v164, v198
	v_fma_f32 v214, v71, v165, v214
	v_fma_f32 v165, v68, v165, v198
	v_fma_f32 v164, v68, v164, v214
	v_fma_f32 v199, -v71, v164, v199
	v_fma_f32 v215, v71, v165, v215
	v_fma_f32 v165, v68, v165, v199
	v_fma_f32 v164, v68, v164, v215
	v_fma_f32 v8, -v71, v164, v8
	v_fma_f32 v144, v71, v165, v144
	v_fma_f32 v165, v68, v165, v8
	v_fma_f32 v164, v68, v164, v144
	v_fma_f32 v9, -v71, v164, v9
	v_fma_f32 v145, v71, v165, v145
	v_fma_f32 v165, v68, v165, v9
	v_fma_f32 v164, v68, v164, v145
	v_fma_f32 v10, -v71, v164, v10
	v_fma_f32 v146, v71, v165, v146
	v_fma_f32 v165, v68, v165, v10
	v_fma_f32 v164, v68, v164, v146
	v_fma_f32 v11, -v71, v164, v11
	v_fma_f32 v147, v71, v165, v147
	v_fma_f32 v165, v68, v165, v11
	v_fma_f32 v164, v68, v164, v147
	v_fma_f32 v200, -v71, v164, v200
	v_fma_f32 v216, v71, v165, v216
	v_fma_f32 v165, v68, v165, v200
	v_fma_f32 v164, v68, v164, v216
	v_fma_f32 v201, -v71, v164, v201
	v_fma_f32 v217, v71, v165, v217
	v_fma_f32 v165, v68, v165, v201
	v_fma_f32 v164, v68, v164, v217
	v_fma_f32 v202, -v71, v164, v202
	v_fma_f32 v218, v71, v165, v218
	v_fma_f32 v165, v68, v165, v202
	v_fma_f32 v164, v68, v164, v218
	v_fma_f32 v203, -v71, v164, v203
	v_fma_f32 v219, v71, v165, v219
	v_fma_f32 v165, v68, v165, v203
	v_fma_f32 v164, v68, v164, v219
	v_fma_f32 v12, -v71, v164, v12
	v_fma_f32 v148, v71, v165, v148
	v_fma_f32 v165, v68, v165, v12
	v_fma_f32 v164, v68, v164, v148
	v_fma_f32 v13, -v71, v164, v13
	v_fma_f32 v149, v71, v165, v149
	v_fma_f32 v165, v68, v165, v13
	v_fma_f32 v164, v68, v164, v149
	v_fma_f32 v14, -v71, v164, v14
	v_fma_f32 v150, v71, v165, v150
	v_fma_f32 v165, v68, v165, v14
	v_fma_f32 v164, v68, v164, v150
	v_fma_f32 v15, -v71, v164, v15
	v_fma_f32 v151, v71, v165, v151
	v_fma_f32 v165, v68, v165, v15
	v_fma_f32 v164, v68, v164, v151
	v_fma_f32 v204, -v71, v164, v204
	v_fma_f32 v220, v71, v165, v220
	v_fma_f32 v165, v68, v165, v204
	v_fma_f32 v164, v68, v164, v220
	v_fma_f32 v205, -v71, v164, v205
	v_fma_f32 v221, v71, v165, v221
	v_fma_f32 v165, v68, v165, v205
	v_fma_f32 v164, v68, v164, v221
	v_fma_f32 v206, -v71, v164, v206
	v_fma_f32 v222, v71, v165, v222
	v_fma_f32 v165, v68, v165, v206
	v_fma_f32 v164, v68, v164, v222
	v_fma_f32 v207, -v71, v164, v207
	v_fma_f32 v223, v71, v165, v223
	v_fma_f32 v165, v68, v165, v207
	v_fma_f32 v164, v68, v164, v223
	ds_read_b128 v[224:227], v101 offset:64
	global_load_dwordx4 v[60:63], v[128:129], off
	global_load_dwordx4 v[56:59], v[130:131], off
	global_load_dwordx4 v[52:55], v[132:133], off
	global_load_dwordx4 v[48:51], v[134:135], off
	s_waitcnt vmcnt(7) lgkmcnt(0)
; #define LAS __attribute__((address_space(3)))
; template <bool PASS2>
; __device__ __forceinline__ void s5_tile(const Ctx& C, int T, int sb_lo, int sb_hi, LAS unsigned char* lds, int wave, int lane) {
;     ...
;         for (int gi = 0; gi < 4; ++gi) {
;             const int g = wave * 4 + gi, gnx = wave * 4 + ((gi + 1) & 3);
;             bfx8 bb[4], cm[4];
; #pragma unroll
;             for (int cb = 0; cb < 4; ++cb) { bb[cb] = bbn[cb]; bbn[cb] = *(const bfx8*)(BBt + ((size_t)(gnx * 128 + cb * 32 + tl)) * GN + 8 * hh); }
;             if (PASS2) {
; #pragma unroll
;                 for (int ks = 0; ks < 4; ++ks) { cm[ks] = cmn[ks]; cmn[ks] = *(const bfx8*)(CMt + ((size_t)(gnx * GN + fr)) * 128 + 32 * ks + 8 * kq); }
;             }
;             float s0ar = 0.f, s0ai = 0.f, s0br = 0.f, s0bi = 0.f;
;             if (sample) { const size_t o0 = ((size_t)(2 * sb) * NG + g) * NP + lane, o1 = o0 + (size_t)NG * NP;
;                 s0ar = C.in(2)[o0]; s0ai = C.in(3)[o0]; s0br = C.in(2)[o1]; s0bi = C.in(3)[o1]; }
;             const bfx8 a = *(const LAS bfx8*)(XU + tl * XU_STRIDE + 16 * gi + 8 * hh);
; #pragma unroll
;             for (int cb = 0; cb < 4; ++cb) {
;                 v16f acc;
; #pragma unroll
;                 for (int r = 0; r < 16; ++r) acc[r] = 0.f;
;                 acc = __builtin_amdgcn_mfma_f32_32x32x16_bf16(bb[cb], a, acc, 0, 0, 0);
; #pragma unroll
;                 for (int rg = 0; rg < 4; ++rg) { v2u w; w.x = cvt_pk_c(acc[4 * rg], acc[4 * rg + 1]); w.y = cvt_pk_c(acc[4 * rg + 2], acc[4 * rg + 3]);
;                     *(LAS v2u*)(BH + tl * BH_STRIDE + cb * 32 + 8 * rg + 4 * hh) = w; }
;             }
;             LDS_FENCE();
;             {
;                 unsigned bu[32];
; #pragma unroll
;                 for (int t = 0; t < 32; ++t) bu[t] = *(const LAS unsigned*)(BH + t * BH_STRIDE + 2 * lane);
;                 LDS_FENCE();
;                 float xr = sr[gi], xi = si[gi];
; #pragma unroll
;                 for (int t = 0; t < 32; ++t) {
;                     if (sample && t == 0) { xr = s0ar; xi = s0ai; }
;                     if (sample && t == 16) { xr = s0br; xi = s0bi; }
;                     const float nr = fmaf(lr[gi], xr, fmaf(-li[gi], xi, bf_lo(bu[t]))), ni = fmaf(lr[gi], xi, fmaf(li[gi], xr, bf_hi(bu[t])));
;                     xr = nr; xi = ni;
;                     if (PASS2) {
	v_mfma_f32_32x32x16_bf16 v[0:15], v[224:227], v[44:47], 0
	s_waitcnt vmcnt(6)
	v_mfma_f32_32x32x16_bf16 v[136:151], v[224:227], v[40:43], 0
	s_waitcnt vmcnt(5)
	v_mfma_f32_32x32x16_bf16 v[192:207], v[224:227], v[36:39], 0
	s_waitcnt vmcnt(4)
	v_mfma_f32_32x32x16_bf16 v[208:223], v[224:227], v[32:35], 0
	s_nop 11
	v_permlane32_swap_b32_e32 v0, v192
	v_permlane32_swap_b32_e32 v1, v193
	v_permlane32_swap_b32_e32 v2, v194
	v_permlane32_swap_b32_e32 v3, v195
	v_permlane32_swap_b32_e32 v4, v196
	v_permlane32_swap_b32_e32 v5, v197
	v_permlane32_swap_b32_e32 v6, v198
	v_permlane32_swap_b32_e32 v7, v199
	v_permlane32_swap_b32_e32 v8, v200
	v_permlane32_swap_b32_e32 v9, v201
	v_permlane32_swap_b32_e32 v10, v202
	v_permlane32_swap_b32_e32 v11, v203
	v_permlane32_swap_b32_e32 v12, v204
	v_permlane32_swap_b32_e32 v13, v205
	v_permlane32_swap_b32_e32 v14, v206
	v_permlane32_swap_b32_e32 v15, v207
	v_permlane32_swap_b32_e32 v136, v208
	v_permlane32_swap_b32_e32 v137, v209
	v_permlane32_swap_b32_e32 v138, v210
	v_permlane32_swap_b32_e32 v139, v211
	v_permlane32_swap_b32_e32 v140, v212
	v_permlane32_swap_b32_e32 v141, v213
	v_permlane32_swap_b32_e32 v142, v214
	v_permlane32_swap_b32_e32 v143, v215
	v_permlane32_swap_b32_e32 v144, v216
	v_permlane32_swap_b32_e32 v145, v217
	v_permlane32_swap_b32_e32 v146, v218
	v_permlane32_swap_b32_e32 v147, v219
	v_permlane32_swap_b32_e32 v148, v220
	v_permlane32_swap_b32_e32 v149, v221
	v_permlane32_swap_b32_e32 v150, v222
	v_permlane32_swap_b32_e32 v151, v223
	v_fma_f32 v0, -v75, v162, v0
	v_fma_f32 v136, v75, v163, v136
	v_fma_f32 v163, v72, v163, v0
	v_fma_f32 v162, v72, v162, v136
	v_fma_f32 v1, -v75, v162, v1
	v_fma_f32 v137, v75, v163, v137
	v_fma_f32 v163, v72, v163, v1
	v_fma_f32 v162, v72, v162, v137
	v_fma_f32 v2, -v75, v162, v2
	v_fma_f32 v138, v75, v163, v138
	v_fma_f32 v163, v72, v163, v2
	v_fma_f32 v162, v72, v162, v138
	v_fma_f32 v3, -v75, v162, v3
	v_fma_f32 v139, v75, v163, v139
	v_fma_f32 v163, v72, v163, v3
	v_fma_f32 v162, v72, v162, v139
	v_fma_f32 v192, -v75, v162, v192
	v_fma_f32 v208, v75, v163, v208
	v_fma_f32 v163, v72, v163, v192
	v_fma_f32 v162, v72, v162, v208
	v_fma_f32 v193, -v75, v162, v193
	v_fma_f32 v209, v75, v163, v209
	v_fma_f32 v163, v72, v163, v193
	v_fma_f32 v162, v72, v162, v209
	v_fma_f32 v194, -v75, v162, v194
	v_fma_f32 v210, v75, v163, v210
	v_fma_f32 v163, v72, v163, v194
	v_fma_f32 v162, v72, v162, v210
	v_fma_f32 v195, -v75, v162, v195
	v_fma_f32 v211, v75, v163, v211
	v_fma_f32 v163, v72, v163, v195
	v_fma_f32 v162, v72, v162, v211
	v_fma_f32 v4, -v75, v162, v4
	v_fma_f32 v140, v75, v163, v140
	v_fma_f32 v163, v72, v163, v4
	v_fma_f32 v162, v72, v162, v140
	v_fma_f32 v5, -v75, v162, v5
	v_fma_f32 v141, v75, v163, v141
	v_fma_f32 v163, v72, v163, v5
	v_fma_f32 v162, v72, v162, v141
	v_fma_f32 v6, -v75, v162, v6
	v_fma_f32 v142, v75, v163, v142
	v_fma_f32 v163, v72, v163, v6
	v_fma_f32 v162, v72, v162, v142
	v_fma_f32 v7, -v75, v162, v7
	v_fma_f32 v143, v75, v163, v143
	v_fma_f32 v163, v72, v163, v7
	v_fma_f32 v162, v72, v162, v143
	v_fma_f32 v196, -v75, v162, v196
	v_fma_f32 v212, v75, v163, v212
	v_fma_f32 v163, v72, v163, v196
	v_fma_f32 v162, v72, v162, v212
	v_fma_f32 v197, -v75, v162, v197
	v_fma_f32 v213, v75, v163, v213
	v_fma_f32 v163, v72, v163, v197
	v_fma_f32 v162, v72, v162, v213
	v_fma_f32 v198, -v75, v162, v198
	v_fma_f32 v214, v75, v163, v214
	v_fma_f32 v163, v72, v163, v198
	v_fma_f32 v162, v72, v162, v214
	v_fma_f32 v199, -v75, v162, v199
	v_fma_f32 v215, v75, v163, v215
	v_fma_f32 v163, v72, v163, v199
	v_fma_f32 v162, v72, v162, v215
	v_fma_f32 v8, -v75, v162, v8
	v_fma_f32 v144, v75, v163, v144
	v_fma_f32 v163, v72, v163, v8
	v_fma_f32 v162, v72, v162, v144
	v_fma_f32 v9, -v75, v162, v9
	v_fma_f32 v145, v75, v163, v145
	v_fma_f32 v163, v72, v163, v9
	v_fma_f32 v162, v72, v162, v145
	v_fma_f32 v10, -v75, v162, v10
	v_fma_f32 v146, v75, v163, v146
	v_fma_f32 v163, v72, v163, v10
	v_fma_f32 v162, v72, v162, v146
	v_fma_f32 v11, -v75, v162, v11
	v_fma_f32 v147, v75, v163, v147
	v_fma_f32 v163, v72, v163, v11
	v_fma_f32 v162, v72, v162, v147
	v_fma_f32 v200, -v75, v162, v200
	v_fma_f32 v216, v75, v163, v216
	v_fma_f32 v163, v72, v163, v200
	v_fma_f32 v162, v72, v162, v216
	v_fma_f32 v201, -v75, v162, v201
	v_fma_f32 v217, v75, v163, v217
	v_fma_f32 v163, v72, v163, v201
	v_fma_f32 v162, v72, v162, v217
	v_fma_f32 v202, -v75, v162, v202
	v_fma_f32 v218, v75, v163, v218
	v_fma_f32 v163, v72, v163, v202
	v_fma_f32 v162, v72, v162, v218
	v_fma_f32 v203, -v75, v162, v203
	v_fma_f32 v219, v75, v163, v219
	v_fma_f32 v163, v72, v163, v203
	v_fma_f32 v162, v72, v162, v219
	v_fma_f32 v12, -v75, v162, v12
	v_fma_f32 v148, v75, v163, v148
	v_fma_f32 v163, v72, v163, v12
	v_fma_f32 v162, v72, v162, v148
	v_fma_f32 v13, -v75, v162, v13
	v_fma_f32 v149, v75, v163, v149
	v_fma_f32 v163, v72, v163, v13
	v_fma_f32 v162, v72, v162, v149
	v_fma_f32 v14, -v75, v162, v14
	v_fma_f32 v150, v75, v163, v150
	v_fma_f32 v163, v72, v163, v14
	v_fma_f32 v162, v72, v162, v150
	v_fma_f32 v15, -v75, v162, v15
	v_fma_f32 v151, v75, v163, v151
	v_fma_f32 v163, v72, v163, v15
	v_fma_f32 v162, v72, v162, v151
	v_fma_f32 v204, -v75, v162, v204
	v_fma_f32 v220, v75, v163, v220
	v_fma_f32 v163, v72, v163, v204
	v_fma_f32 v162, v72, v162, v220
	v_fma_f32 v205, -v75, v162, v205
	v_fma_f32 v221, v75, v163, v221
	v_fma_f32 v163, v72, v163, v205
	v_fma_f32 v162, v72, v162, v221
	v_fma_f32 v206, -v75, v162, v206
	v_fma_f32 v222, v75, v163, v222
	v_fma_f32 v163, v72, v163, v206
	v_fma_f32 v162, v72, v162, v222
	v_fma_f32 v207, -v75, v162, v207
	v_fma_f32 v223, v75, v163, v223
	v_fma_f32 v163, v72, v163, v207
	v_fma_f32 v162, v72, v162, v223
	ds_read_b128 v[228:231], v101 offset:96
	global_load_dwordx4 v[44:47], v[104:105], off
	global_load_dwordx4 v[40:43], v[106:107], off
	global_load_dwordx4 v[36:39], v[108:109], off
	global_load_dwordx4 v[32:35], v[110:111], off
	s_waitcnt vmcnt(7) lgkmcnt(0)
; #define LAS __attribute__((address_space(3)))
; template <bool PASS2>
; __device__ __forceinline__ void s5_tile(const Ctx& C, int T, int sb_lo, int sb_hi, LAS unsigned char* lds, int wave, int lane) {
;     ...
;         for (int gi = 0; gi < 4; ++gi) {
;             const int g = wave * 4 + gi, gnx = wave * 4 + ((gi + 1) & 3);
;             bfx8 bb[4], cm[4];
; #pragma unroll
;             for (int cb = 0; cb < 4; ++cb) { bb[cb] = bbn[cb]; bbn[cb] = *(const bfx8*)(BBt + ((size_t)(gnx * 128 + cb * 32 + tl)) * GN + 8 * hh); }
;             if (PASS2) {
; #pragma unroll
;                 for (int ks = 0; ks < 4; ++ks) { cm[ks] = cmn[ks]; cmn[ks] = *(const bfx8*)(CMt + ((size_t)(gnx * GN + fr)) * 128 + 32 * ks + 8 * kq); }
;             }
;             float s0ar = 0.f, s0ai = 0.f, s0br = 0.f, s0bi = 0.f;
;             if (sample) { const size_t o0 = ((size_t)(2 * sb) * NG + g) * NP + lane, o1 = o0 + (size_t)NG * NP;
;                 s0ar = C.in(2)[o0]; s0ai = C.in(3)[o0]; s0br = C.in(2)[o1]; s0bi = C.in(3)[o1]; }
;             const bfx8 a = *(const LAS bfx8*)(XU + tl * XU_STRIDE + 16 * gi + 8 * hh);
; #pragma unroll
;             for (int cb = 0; cb < 4; ++cb) {
;                 v16f acc;
; #pragma unroll
;                 for (int r = 0; r < 16; ++r) acc[r] = 0.f;
;                 acc = __builtin_amdgcn_mfma_f32_32x32x16_bf16(bb[cb], a, acc, 0, 0, 0);
; #pragma unroll
;                 for (int rg = 0; rg < 4; ++rg) { v2u w; w.x = cvt_pk_c(acc[4 * rg], acc[4 * rg + 1]); w.y = cvt_pk_c(acc[4 * rg + 2], acc[4 * rg + 3]);
;                     *(LAS v2u*)(BH + tl * BH_STRIDE + cb * 32 + 8 * rg + 4 * hh) = w; }
;             }
;             LDS_FENCE();
;             {
;                 unsigned bu[32];
; #pragma unroll
;                 for (int t = 0; t < 32; ++t) bu[t] = *(const LAS unsigned*)(BH + t * BH_STRIDE + 2 * lane);
;                 LDS_FENCE();
;                 float xr = sr[gi], xi = si[gi];
; #pragma unroll
;                 for (int t = 0; t < 32; ++t) {
;                     if (sample && t == 0) { xr = s0ar; xi = s0ai; }
;                     if (sample && t == 16) { xr = s0br; xi = s0bi; }
;                     const float nr = fmaf(lr[gi], xr, fmaf(-li[gi], xi, bf_lo(bu[t]))), ni = fmaf(lr[gi], xi, fmaf(li[gi], xr, bf_hi(bu[t])));
;                     xr = nr; xi = ni;
;                     if (PASS2) {
	v_mfma_f32_32x32x16_bf16 v[0:15], v[228:231], v[60:63], 0
	s_waitcnt vmcnt(6)
	v_mfma_f32_32x32x16_bf16 v[136:151], v[228:231], v[56:59], 0
	s_waitcnt vmcnt(5)
	v_mfma_f32_32x32x16_bf16 v[192:207], v[228:231], v[52:55], 0
	s_waitcnt vmcnt(4)
	v_mfma_f32_32x32x16_bf16 v[208:223], v[228:231], v[48:51], 0
	s_nop 11
	v_permlane32_swap_b32_e32 v0, v192
	v_permlane32_swap_b32_e32 v1, v193
	v_permlane32_swap_b32_e32 v2, v194
	v_permlane32_swap_b32_e32 v3, v195
	v_permlane32_swap_b32_e32 v4, v196
	v_permlane32_swap_b32_e32 v5, v197
	v_permlane32_swap_b32_e32 v6, v198
	v_permlane32_swap_b32_e32 v7, v199
	v_permlane32_swap_b32_e32 v8, v200
	v_permlane32_swap_b32_e32 v9, v201
	v_permlane32_swap_b32_e32 v10, v202
	v_permlane32_swap_b32_e32 v11, v203
	v_permlane32_swap_b32_e32 v12, v204
	v_permlane32_swap_b32_e32 v13, v205
	v_permlane32_swap_b32_e32 v14, v206
	v_permlane32_swap_b32_e32 v15, v207
	v_permlane32_swap_b32_e32 v136, v208
	v_permlane32_swap_b32_e32 v137, v209
	v_permlane32_swap_b32_e32 v138, v210
	v_permlane32_swap_b32_e32 v139, v211
	v_permlane32_swap_b32_e32 v140, v212
	v_permlane32_swap_b32_e32 v141, v213
	v_permlane32_swap_b32_e32 v142, v214
	v_permlane32_swap_b32_e32 v143, v215
	v_permlane32_swap_b32_e32 v144, v216
	v_permlane32_swap_b32_e32 v145, v217
	v_permlane32_swap_b32_e32 v146, v218
	v_permlane32_swap_b32_e32 v147, v219
	v_permlane32_swap_b32_e32 v148, v220
	v_permlane32_swap_b32_e32 v149, v221
	v_permlane32_swap_b32_e32 v150, v222
	v_permlane32_swap_b32_e32 v151, v223
	v_fma_f32 v0, -v79, v160, v0
	v_fma_f32 v136, v79, v161, v136
	v_fma_f32 v161, v76, v161, v0
	v_fma_f32 v160, v76, v160, v136
	v_fma_f32 v1, -v79, v160, v1
	v_fma_f32 v137, v79, v161, v137
	v_fma_f32 v161, v76, v161, v1
	v_fma_f32 v160, v76, v160, v137
	v_fma_f32 v2, -v79, v160, v2
	v_fma_f32 v138, v79, v161, v138
	v_fma_f32 v161, v76, v161, v2
	v_fma_f32 v160, v76, v160, v138
	v_fma_f32 v3, -v79, v160, v3
	v_fma_f32 v139, v79, v161, v139
	v_fma_f32 v161, v76, v161, v3
	v_fma_f32 v160, v76, v160, v139
	v_fma_f32 v192, -v79, v160, v192
	v_fma_f32 v208, v79, v161, v208
	v_fma_f32 v161, v76, v161, v192
	v_fma_f32 v160, v76, v160, v208
	v_fma_f32 v193, -v79, v160, v193
	v_fma_f32 v209, v79, v161, v209
	v_fma_f32 v161, v76, v161, v193
	v_fma_f32 v160, v76, v160, v209
	v_fma_f32 v194, -v79, v160, v194
	v_fma_f32 v210, v79, v161, v210
	v_fma_f32 v161, v76, v161, v194
	v_fma_f32 v160, v76, v160, v210
	v_fma_f32 v195, -v79, v160, v195
	v_fma_f32 v211, v79, v161, v211
	v_fma_f32 v161, v76, v161, v195
	v_fma_f32 v160, v76, v160, v211
	v_fma_f32 v4, -v79, v160, v4
	v_fma_f32 v140, v79, v161, v140
	v_fma_f32 v161, v76, v161, v4
	v_fma_f32 v160, v76, v160, v140
	v_fma_f32 v5, -v79, v160, v5
	v_fma_f32 v141, v79, v161, v141
	v_fma_f32 v161, v76, v161, v5
	v_fma_f32 v160, v76, v160, v141
	v_fma_f32 v6, -v79, v160, v6
	v_fma_f32 v142, v79, v161, v142
	v_fma_f32 v161, v76, v161, v6
	v_fma_f32 v160, v76, v160, v142
	v_fma_f32 v7, -v79, v160, v7
	v_fma_f32 v143, v79, v161, v143
	v_fma_f32 v161, v76, v161, v7
	v_fma_f32 v160, v76, v160, v143
	v_fma_f32 v196, -v79, v160, v196
	v_fma_f32 v212, v79, v161, v212
	v_fma_f32 v161, v76, v161, v196
	v_fma_f32 v160, v76, v160, v212
	v_fma_f32 v197, -v79, v160, v197
	v_fma_f32 v213, v79, v161, v213
	v_fma_f32 v161, v76, v161, v197
	v_fma_f32 v160, v76, v160, v213
	v_fma_f32 v198, -v79, v160, v198
	v_fma_f32 v214, v79, v161, v214
	v_fma_f32 v161, v76, v161, v198
	v_fma_f32 v160, v76, v160, v214
	v_fma_f32 v199, -v79, v160, v199
	v_fma_f32 v215, v79, v161, v215
	v_fma_f32 v161, v76, v161, v199
	v_fma_f32 v160, v76, v160, v215
	v_fma_f32 v8, -v79, v160, v8
	v_fma_f32 v144, v79, v161, v144
	v_fma_f32 v161, v76, v161, v8
	v_fma_f32 v160, v76, v160, v144
	v_fma_f32 v9, -v79, v160, v9
	v_fma_f32 v145, v79, v161, v145
	v_fma_f32 v161, v76, v161, v9
	v_fma_f32 v160, v76, v160, v145
	v_fma_f32 v10, -v79, v160, v10
	v_fma_f32 v146, v79, v161, v146
	v_fma_f32 v161, v76, v161, v10
	v_fma_f32 v160, v76, v160, v146
	v_fma_f32 v11, -v79, v160, v11
	v_fma_f32 v147, v79, v161, v147
	v_fma_f32 v161, v76, v161, v11
	v_fma_f32 v160, v76, v160, v147
	v_fma_f32 v200, -v79, v160, v200
	v_fma_f32 v216, v79, v161, v216
	v_fma_f32 v161, v76, v161, v200
	v_fma_f32 v160, v76, v160, v216
	v_fma_f32 v201, -v79, v160, v201
	v_fma_f32 v217, v79, v161, v217
	v_fma_f32 v161, v76, v161, v201
	v_fma_f32 v160, v76, v160, v217
	v_fma_f32 v202, -v79, v160, v202
	v_fma_f32 v218, v79, v161, v218
	v_fma_f32 v161, v76, v161, v202
	v_fma_f32 v160, v76, v160, v218
	v_fma_f32 v203, -v79, v160, v203
	v_fma_f32 v219, v79, v161, v219
	v_fma_f32 v161, v76, v161, v203
	v_fma_f32 v160, v76, v160, v219
	v_fma_f32 v12, -v79, v160, v12
	v_fma_f32 v148, v79, v161, v148
	v_fma_f32 v161, v76, v161, v12
	v_fma_f32 v160, v76, v160, v148
	v_fma_f32 v13, -v79, v160, v13
	v_fma_f32 v149, v79, v161, v149
	v_fma_f32 v161, v76, v161, v13
	v_fma_f32 v160, v76, v160, v149
	v_fma_f32 v14, -v79, v160, v14
	v_fma_f32 v150, v79, v161, v150
	v_fma_f32 v161, v76, v161, v14
	v_fma_f32 v160, v76, v160, v150
	v_fma_f32 v15, -v79, v160, v15
	v_fma_f32 v151, v79, v161, v151
	v_fma_f32 v161, v76, v161, v15
	v_fma_f32 v160, v76, v160, v151
	v_fma_f32 v204, -v79, v160, v204
	v_fma_f32 v220, v79, v161, v220
	v_fma_f32 v161, v76, v161, v204
	v_fma_f32 v160, v76, v160, v220
	v_fma_f32 v205, -v79, v160, v205
	v_fma_f32 v221, v79, v161, v221
	v_fma_f32 v161, v76, v161, v205
	v_fma_f32 v160, v76, v160, v221
	v_fma_f32 v206, -v79, v160, v206
	v_fma_f32 v222, v79, v161, v222
	v_fma_f32 v161, v76, v161, v206
	v_fma_f32 v160, v76, v160, v222
	v_fma_f32 v207, -v79, v160, v207
	v_fma_f32 v223, v79, v161, v223
	v_fma_f32 v161, v76, v161, v207
	v_fma_f32 v160, v76, v160, v223
	s_add_i32 s25, s25, 32
	s_cmpk_lg_i32 s25, 0x80
	s_cbranch_scc0 .LBB0_599
